# GU epilogue: wr==0 alignment barrier moved after the second output row (deeper head start for the leading wave half)
# baseline (speedup 1.0000x reference)
; #define LAS __attribute__((address_space(3)))
; #define PG8_BAR __builtin_amdgcn_s_barrier()
; #define ROW_RS(u, ai, m) row_rs_lds((ai) * 128 + wr * 64 + (m) * 16 + fr, fq)
; #define ROWLOOP for (int ai = 0; ai < 2; ++ai) _Pragma("unroll") for (int m = 0; m < 4; ++m)
; template <class Epi>
; __device__ __forceinline__ void gemm_phase(LAS unsigned char* lds, const int tid, const Gemm g, const StaticOrder& S, const Epi& E) {
;     ...
;         if (wr == 0) PG8_BAR;
; __device__ __forceinline__ float row_rs_lds(int rt, int fq) {
;     extern __shared__ __attribute__((aligned(16))) unsigned char lds_raw_[];
;     const f32x4 v = *(const LAS f32x4*)((LAS unsigned char*)lds_raw_ + RS_OFF + rt * 64 + fq * 16);
;     float s = (v[0] + v[1]) + (v[2] + v[3]);
;     s = red4_sum(s);
;     return __builtin_amdgcn_rsqf(s * (1.0f / D) + EPS);
; }
;     __device__ __forceinline__ void operator()(const Acc& acc, const Unit& u, int wr, int wc, int fr, int fq) const {
;         const int col0 = u.pn * 128 + wc * 32 + fq * 8;
; #pragma unroll
;         ROWLOOP {
;             const int row = ROW_OF(u, ai, m); const float rs = ROW_RS(u, ai, m); const float c1 = -rs * LOG2E, rs2 = rs * rs;
;             f32x4 o[2];
; #pragma unroll
;             for (int n = 0; n < 2; ++n) {
;                 const f32x4 gv = acc[ai][0][m][n], gu = gv * acc[ai][1][m][n], t = gv * c1; f32x4 r;
; #pragma unroll
;                 for (int e = 0; e < 4; ++e) r[e] = __builtin_amdgcn_rcpf(1.0f + __builtin_amdgcn_exp2f(t[e]));
;                 o[n] = gu * (r * rs2);
;             }
;             *(u32x4*)(act + (size_t)row * FF + col0) = pack8(o[0], o[1]);
;         }
.LBB0_266:
.LBB0_268:
	ds_read_b128 v[188:191], v154
	ds_read_b128 v[192:195], v154 offset:1024
	ds_read_b128 v[196:199], v154 offset:2048
	ds_read_b128 v[200:203], v154 offset:3072
	ds_read_b128 v[204:207], v154 offset:8192
	ds_read_b128 v[208:211], v154 offset:9216
	ds_read_b128 v[212:215], v154 offset:10240
	ds_read_b128 v[216:219], v154 offset:11264
	v_pk_mul_f32 v[112:113], v[112:113], v[116:117]
	v_pk_mul_f32 v[114:115], v[114:115], v[118:119]
	v_pk_mul_f32 v[104:105], v[104:105], v[108:109]
	v_pk_mul_f32 v[106:107], v[106:107], v[110:111]
	s_waitcnt lgkmcnt(7)
	v_add_f32_e32 v146, v188, v189
	v_add_f32_e32 v147, v190, v191
	v_add_f32_e32 v146, v146, v147
	v_mov_b32_e32 v147, v146
	s_nop 1
	v_permlane16_swap_b32_e32 v146, v147
	v_add_f32_e32 v146, v146, v147
	v_mov_b32_e32 v147, v146
	s_nop 1
	v_permlane32_swap_b32_e32 v146, v147
	v_add_f32_e32 v146, v146, v147
	v_fmamk_f32 v146, v146, 0x3a800000, v155
	v_rsq_f32_e32 v147, v146
	v_lshl_or_b32 v148, s54, 7, v152
	v_lshl_add_u32 v146, s24, 8, v150
	v_pk_mul_f32 v[96:97], v[96:97], v[100:101]
	v_mul_f32_e32 v156, 0xbfb8aa3b, v147
	v_pk_mul_f32 v[160:161], v[120:121], v[156:157] op_sel_hi:[1,0]
	v_mul_f32_e32 v158, v147, v147
	v_exp_f32_e32 v147, v160
	v_exp_f32_e32 v149, v161
	v_pk_mul_f32 v[160:161], v[122:123], v[156:157] op_sel_hi:[1,0]
	v_pk_mul_f32 v[120:121], v[124:125], v[120:121]
	v_add_f32_e32 v147, 1.0, v147
	v_exp_f32_e32 v157, v160
	v_rcp_f32_e32 v160, v147
	v_exp_f32_e32 v147, v161
	v_add_f32_e32 v149, 1.0, v149
	v_rcp_f32_e32 v161, v149
	v_add_f32_e32 v149, 1.0, v157
	v_add_f32_e32 v147, 1.0, v147
	v_rcp_f32_e32 v162, v149
	v_rcp_f32_e32 v163, v147
	v_pk_mul_f32 v[122:123], v[126:127], v[122:123]
	v_pk_mul_f32 v[124:125], v[158:159], v[160:161] op_sel_hi:[0,1]
	v_pk_mul_f32 v[120:121], v[120:121], v[124:125]
	v_pk_mul_f32 v[126:127], v[158:159], v[162:163] op_sel_hi:[0,1]
	v_pk_mul_f32 v[122:123], v[122:123], v[126:127]
	v_pk_mul_f32 v[126:127], v[116:117], v[156:157] op_sel_hi:[1,0]
	v_pk_mul_f32 v[124:125], v[118:119], v[156:157] op_sel_hi:[1,0]
	v_exp_f32_e32 v126, v126
	v_exp_f32_e32 v127, v127
	v_exp_f32_e32 v124, v124
	v_exp_f32_e32 v125, v125
	v_add_f32_e32 v126, 1.0, v126
	v_add_f32_e32 v127, 1.0, v127
	v_add_f32_e32 v124, 1.0, v124
	v_add_f32_e32 v125, 1.0, v125
	v_rcp_f32_e32 v126, v126
	v_rcp_f32_e32 v127, v127
	v_rcp_f32_e32 v124, v124
	v_rcp_f32_e32 v125, v125
	v_ashrrev_i32_e32 v149, 31, v148
	v_pk_mul_f32 v[116:117], v[158:159], v[126:127] op_sel_hi:[0,1]
	v_pk_mul_f32 v[112:113], v[112:113], v[116:117]
	v_pk_mul_f32 v[118:119], v[158:159], v[124:125] op_sel_hi:[0,1]
	v_pk_mul_f32 v[114:115], v[114:115], v[118:119]
	v_cvt_pk_bf16_f32 v116, v120, v121
	v_cvt_pk_bf16_f32 v117, v122, v123
	v_cvt_pk_bf16_f32 v118, v112, v113
	v_mov_b64_e32 v[112:113], s[10:11]
	v_cvt_pk_bf16_f32 v119, v114, v115
	v_mad_i64_i32 v[124:125], s[24:25], v146, s53, v[112:113]
	v_pk_mul_f32 v[98:99], v[98:99], v[102:103]
	v_pk_mul_f32 v[88:89], v[88:89], v[92:93]
	s_waitcnt lgkmcnt(6)
	v_add_f32_e32 v114, v192, v193
	v_add_f32_e32 v115, v194, v195
	v_add_f32_e32 v114, v114, v115
	v_mov_b32_e32 v115, v114
	s_nop 1
	v_permlane16_swap_b32_e32 v114, v115
	v_add_f32_e32 v114, v114, v115
	v_mov_b32_e32 v115, v114
	s_nop 1
	v_permlane32_swap_b32_e32 v114, v115
	v_add_f32_e32 v114, v114, v115
	v_fmamk_f32 v114, v114, 0x3a800000, v155
	v_rsq_f32_e32 v122, v114
	v_lshlrev_b64 v[114:115], 1, v[148:149]
	v_lshl_add_u64 v[120:121], v[124:125], 0, v[114:115]
	global_store_dwordx4 v[120:121], v[116:119], off
	v_pk_mul_f32 v[90:91], v[90:91], v[94:95]
	v_pk_mul_f32 v[80:81], v[80:81], v[84:85]
	v_mul_f32_e32 v116, 0xbfb8aa3b, v122
	v_pk_mul_f32 v[118:119], v[108:109], v[116:117] op_sel_hi:[1,0]
	v_pk_mul_f32 v[82:83], v[82:83], v[86:87]
	v_exp_f32_e32 v117, v118
	v_mul_f32_e32 v118, v122, v122
	v_exp_f32_e32 v119, v119
	v_pk_mul_f32 v[72:73], v[72:73], v[76:77]
	v_pk_mul_f32 v[120:121], v[110:111], v[116:117] op_sel_hi:[1,0]
	v_add_f32_e32 v117, 1.0, v117
	v_rcp_f32_e32 v122, v117
	v_exp_f32_e32 v117, v120
	v_exp_f32_e32 v121, v121
	v_add_f32_e32 v119, 1.0, v119
	v_rcp_f32_e32 v123, v119
	v_add_f32_e32 v117, 1.0, v117
	v_rcp_f32_e32 v120, v117
	v_add_f32_e32 v117, 1.0, v121
	v_rcp_f32_e32 v121, v117
	v_pk_mul_f32 v[108:109], v[118:119], v[122:123] op_sel_hi:[0,1]
	v_pk_mul_f32 v[104:105], v[104:105], v[108:109]
	v_pk_mul_f32 v[108:109], v[102:103], v[116:117] op_sel_hi:[1,0]
	v_pk_mul_f32 v[110:111], v[118:119], v[120:121] op_sel_hi:[0,1]
	v_pk_mul_f32 v[106:107], v[106:107], v[110:111]
	v_pk_mul_f32 v[110:111], v[100:101], v[116:117] op_sel_hi:[1,0]
	v_exp_f32_e32 v108, v108
	v_exp_f32_e32 v110, v110
	v_exp_f32_e32 v111, v111
	v_exp_f32_e32 v109, v109
	v_add_f32_e32 v108, 1.0, v108
	v_add_f32_e32 v110, 1.0, v110
	v_add_f32_e32 v111, 1.0, v111
	v_add_f32_e32 v109, 1.0, v109
	v_rcp_f32_e32 v110, v110
	v_rcp_f32_e32 v111, v111
	v_rcp_f32_e32 v108, v108
	v_rcp_f32_e32 v109, v109
	v_pk_mul_f32 v[74:75], v[74:75], v[78:79]
	v_pk_mul_f32 v[100:101], v[118:119], v[110:111] op_sel_hi:[0,1]
	v_pk_mul_f32 v[64:65], v[64:65], v[68:69]
	v_pk_mul_f32 v[102:103], v[118:119], v[108:109] op_sel_hi:[0,1]
	v_pk_mul_f32 v[102:103], v[98:99], v[102:103]
	v_pk_mul_f32 v[98:99], v[96:97], v[100:101]
	v_cvt_pk_bf16_f32 v96, v104, v105
	v_cvt_pk_bf16_f32 v97, v106, v107
	v_or_b32_e32 v104, 16, v146
	v_cvt_pk_bf16_f32 v98, v98, v99
	v_cvt_pk_bf16_f32 v99, v102, v103
	v_pk_mul_f32 v[66:67], v[66:67], v[70:71]
	v_pk_mul_f32 v[56:57], v[56:57], v[60:61]
	v_pk_mul_f32 v[58:59], v[58:59], v[62:63]
	v_pk_mul_f32 v[48:49], v[48:49], v[52:53]
	s_waitcnt lgkmcnt(5)
	v_add_f32_e32 v100, v196, v197
	v_add_f32_e32 v101, v198, v199
	v_add_f32_e32 v100, v100, v101
	v_mov_b32_e32 v101, v100
	s_nop 1
	v_permlane16_swap_b32_e32 v100, v101
	v_add_f32_e32 v100, v100, v101
	v_mov_b32_e32 v101, v100
	s_nop 1
	v_permlane32_swap_b32_e32 v100, v101
	v_add_f32_e32 v100, v100, v101
	v_fmamk_f32 v100, v100, 0x3a800000, v155
	v_rsq_f32_e32 v102, v100
	v_mad_i64_i32 v[100:101], s[24:25], v104, s53, v[112:113]
	v_lshl_add_u64 v[100:101], v[100:101], 0, v[114:115]
	global_store_dwordx4 v[100:101], v[96:99], off
	s_and_b64 vcc, exec, s[6:7]
	s_cbranch_vccz .Lalb_1
	s_barrier
; #define LAS __attribute__((address_space(3)))
; #define ROW_RS(u, ai, m) row_rs_lds((ai) * 128 + wr * 64 + (m) * 16 + fr, fq)
; #define ROWLOOP for (int ai = 0; ai < 2; ++ai) _Pragma("unroll") for (int m = 0; m < 4; ++m)
; __device__ __forceinline__ float row_rs_lds(int rt, int fq) {
;     extern __shared__ __attribute__((aligned(16))) unsigned char lds_raw_[];
;     const f32x4 v = *(const LAS f32x4*)((LAS unsigned char*)lds_raw_ + RS_OFF + rt * 64 + fq * 16);
;     float s = (v[0] + v[1]) + (v[2] + v[3]);
;     s = red4_sum(s);
;     return __builtin_amdgcn_rsqf(s * (1.0f / D) + EPS);
; }
;     __device__ __forceinline__ void operator()(const Acc& acc, const Unit& u, int wr, int wc, int fr, int fq) const {
;         const int col0 = u.pn * 128 + wc * 32 + fq * 8;
; #pragma unroll
;         ROWLOOP {
;             const int row = ROW_OF(u, ai, m); const float rs = ROW_RS(u, ai, m); const float c1 = -rs * LOG2E, rs2 = rs * rs;
;             f32x4 o[2];
; #pragma unroll
;             for (int n = 0; n < 2; ++n) {
;                 const f32x4 gv = acc[ai][0][m][n], gu = gv * acc[ai][1][m][n], t = gv * c1; f32x4 r;
; #pragma unroll
;                 for (int e = 0; e < 4; ++e) r[e] = __builtin_amdgcn_rcpf(1.0f + __builtin_amdgcn_exp2f(t[e]));
;                 o[n] = gu * (r * rs2);
;             }
;             *(u32x4*)(act + (size_t)row * FF + col0) = pack8(o[0], o[1]);
;         }
.Lalb_1:
	v_pk_mul_f32 v[50:51], v[50:51], v[54:55]
	v_pk_mul_f32 v[40:41], v[40:41], v[44:45]
	v_mul_f32_e32 v96, 0xbfb8aa3b, v102
	v_pk_mul_f32 v[98:99], v[92:93], v[96:97] op_sel_hi:[1,0]
	v_pk_mul_f32 v[42:43], v[42:43], v[46:47]
	v_exp_f32_e32 v97, v98
	v_mul_f32_e32 v98, v102, v102
	v_exp_f32_e32 v99, v99
	v_pk_mul_f32 v[32:33], v[32:33], v[36:37]
	v_pk_mul_f32 v[100:101], v[94:95], v[96:97] op_sel_hi:[1,0]
	v_add_f32_e32 v97, 1.0, v97
	v_rcp_f32_e32 v102, v97
	v_exp_f32_e32 v97, v100
	v_exp_f32_e32 v101, v101
	v_add_f32_e32 v99, 1.0, v99
	v_rcp_f32_e32 v103, v99
	v_add_f32_e32 v97, 1.0, v97
	v_rcp_f32_e32 v100, v97
	v_add_f32_e32 v97, 1.0, v101
	v_rcp_f32_e32 v101, v97
	v_pk_mul_f32 v[92:93], v[98:99], v[102:103] op_sel_hi:[0,1]
	v_pk_mul_f32 v[88:89], v[88:89], v[92:93]
	v_pk_mul_f32 v[92:93], v[86:87], v[96:97] op_sel_hi:[1,0]
	v_pk_mul_f32 v[94:95], v[98:99], v[100:101] op_sel_hi:[0,1]
	v_pk_mul_f32 v[90:91], v[90:91], v[94:95]
	v_pk_mul_f32 v[94:95], v[84:85], v[96:97] op_sel_hi:[1,0]
	v_exp_f32_e32 v92, v92
	v_exp_f32_e32 v94, v94
	v_exp_f32_e32 v95, v95
	v_exp_f32_e32 v93, v93
	v_add_f32_e32 v92, 1.0, v92
	v_add_f32_e32 v94, 1.0, v94
	v_add_f32_e32 v95, 1.0, v95
	v_add_f32_e32 v93, 1.0, v93
	v_rcp_f32_e32 v94, v94
	v_rcp_f32_e32 v95, v95
	v_rcp_f32_e32 v92, v92
	v_rcp_f32_e32 v93, v93
	v_pk_mul_f32 v[34:35], v[34:35], v[38:39]
	v_pk_mul_f32 v[84:85], v[98:99], v[94:95] op_sel_hi:[0,1]
	v_pk_mul_f32 v[24:25], v[24:25], v[28:29]
	v_pk_mul_f32 v[86:87], v[98:99], v[92:93] op_sel_hi:[0,1]
	v_pk_mul_f32 v[86:87], v[82:83], v[86:87]
	v_pk_mul_f32 v[82:83], v[80:81], v[84:85]
	v_cvt_pk_bf16_f32 v80, v88, v89
	v_cvt_pk_bf16_f32 v81, v90, v91
	v_or_b32_e32 v88, 32, v146
	v_cvt_pk_bf16_f32 v82, v82, v83
	v_cvt_pk_bf16_f32 v83, v86, v87
	v_pk_mul_f32 v[26:27], v[26:27], v[30:31]
	v_pk_mul_f32 v[16:17], v[16:17], v[20:21]
	v_pk_mul_f32 v[18:19], v[18:19], v[22:23]
	v_pk_mul_f32 v[8:9], v[8:9], v[12:13]
	s_waitcnt lgkmcnt(4)
	v_add_f32_e32 v84, v200, v201
	v_add_f32_e32 v85, v202, v203
	v_add_f32_e32 v84, v84, v85
	v_mov_b32_e32 v85, v84
	s_nop 1
	v_permlane16_swap_b32_e32 v84, v85
	v_add_f32_e32 v84, v84, v85
	v_mov_b32_e32 v85, v84
	s_nop 1
	v_permlane32_swap_b32_e32 v84, v85
	v_add_f32_e32 v84, v84, v85
	v_fmamk_f32 v84, v84, 0x3a800000, v155
	v_rsq_f32_e32 v86, v84
	v_mad_i64_i32 v[84:85], s[24:25], v88, s53, v[112:113]
	v_lshl_add_u64 v[84:85], v[84:85], 0, v[114:115]
	global_store_dwordx4 v[84:85], v[80:83], off
	v_pk_mul_f32 v[10:11], v[10:11], v[14:15]
	v_pk_mul_f32 v[0:1], v[0:1], v[4:5]
	v_mul_f32_e32 v80, 0xbfb8aa3b, v86
	v_pk_mul_f32 v[82:83], v[76:77], v[80:81] op_sel_hi:[1,0]
	v_pk_mul_f32 v[2:3], v[2:3], v[6:7]
	v_exp_f32_e32 v81, v82
	v_mul_f32_e32 v82, v86, v86
	v_exp_f32_e32 v83, v83
	s_andn2_b64 vcc, exec, s[4:5]
	v_pk_mul_f32 v[84:85], v[78:79], v[80:81] op_sel_hi:[1,0]
	v_add_f32_e32 v81, 1.0, v81
	v_rcp_f32_e32 v86, v81
	v_exp_f32_e32 v81, v84
	v_exp_f32_e32 v85, v85
	v_add_f32_e32 v83, 1.0, v83
	v_rcp_f32_e32 v87, v83
	v_add_f32_e32 v81, 1.0, v81
	v_rcp_f32_e32 v84, v81
	v_add_f32_e32 v81, 1.0, v85
	v_rcp_f32_e32 v85, v81
	v_pk_mul_f32 v[76:77], v[82:83], v[86:87] op_sel_hi:[0,1]
	v_pk_mul_f32 v[72:73], v[72:73], v[76:77]
	v_pk_mul_f32 v[76:77], v[70:71], v[80:81] op_sel_hi:[1,0]
	v_pk_mul_f32 v[78:79], v[82:83], v[84:85] op_sel_hi:[0,1]
	v_pk_mul_f32 v[74:75], v[74:75], v[78:79]
	v_pk_mul_f32 v[78:79], v[68:69], v[80:81] op_sel_hi:[1,0]
	v_exp_f32_e32 v76, v76
	v_exp_f32_e32 v78, v78
	v_exp_f32_e32 v79, v79
	v_exp_f32_e32 v77, v77
	v_add_f32_e32 v76, 1.0, v76
	v_add_f32_e32 v78, 1.0, v78
	v_add_f32_e32 v79, 1.0, v79
	v_add_f32_e32 v77, 1.0, v77
	v_rcp_f32_e32 v78, v78
	v_rcp_f32_e32 v79, v79
	v_rcp_f32_e32 v76, v76
	v_rcp_f32_e32 v77, v77
	s_mov_b64 s[4:5], -1
	v_pk_mul_f32 v[68:69], v[82:83], v[78:79] op_sel_hi:[0,1]
	v_pk_mul_f32 v[70:71], v[82:83], v[76:77] op_sel_hi:[0,1]
	v_pk_mul_f32 v[70:71], v[66:67], v[70:71]
	v_pk_mul_f32 v[66:67], v[64:65], v[68:69]
	v_cvt_pk_bf16_f32 v64, v72, v73
	v_cvt_pk_bf16_f32 v65, v74, v75
	v_or_b32_e32 v72, 48, v146
	v_cvt_pk_bf16_f32 v66, v66, v67
	v_cvt_pk_bf16_f32 v67, v70, v71
	s_waitcnt lgkmcnt(3)
	v_add_f32_e32 v68, v204, v205
	v_add_f32_e32 v69, v206, v207
	v_add_f32_e32 v68, v68, v69
	v_mov_b32_e32 v69, v68
	s_nop 1
	v_permlane16_swap_b32_e32 v68, v69
	v_add_f32_e32 v68, v68, v69
	v_mov_b32_e32 v69, v68
	s_nop 1
	v_permlane32_swap_b32_e32 v68, v69
	v_add_f32_e32 v68, v68, v69
	v_fmamk_f32 v68, v68, 0x3a800000, v155
	v_rsq_f32_e32 v70, v68
	v_mad_i64_i32 v[68:69], s[24:25], v72, s53, v[112:113]
	v_lshl_add_u64 v[68:69], v[68:69], 0, v[114:115]
	global_store_dwordx4 v[68:69], v[64:67], off
	s_nop 1
	v_mul_f32_e32 v64, 0xbfb8aa3b, v70
	v_pk_mul_f32 v[66:67], v[60:61], v[64:65] op_sel_hi:[1,0]
	s_nop 0
	v_exp_f32_e32 v65, v66
	v_mul_f32_e32 v66, v70, v70
	v_exp_f32_e32 v67, v67
	v_pk_mul_f32 v[68:69], v[62:63], v[64:65] op_sel_hi:[1,0]
	v_add_f32_e32 v65, 1.0, v65
	v_rcp_f32_e32 v70, v65
	v_exp_f32_e32 v65, v68
	v_exp_f32_e32 v69, v69
	v_add_f32_e32 v67, 1.0, v67
	v_rcp_f32_e32 v71, v67
	v_add_f32_e32 v65, 1.0, v65
	v_rcp_f32_e32 v68, v65
	v_add_f32_e32 v65, 1.0, v69
	v_rcp_f32_e32 v69, v65
	v_pk_mul_f32 v[60:61], v[66:67], v[70:71] op_sel_hi:[0,1]
	v_pk_mul_f32 v[56:57], v[56:57], v[60:61]
	v_pk_mul_f32 v[60:61], v[54:55], v[64:65] op_sel_hi:[1,0]
	v_pk_mul_f32 v[62:63], v[66:67], v[68:69] op_sel_hi:[0,1]
	v_pk_mul_f32 v[58:59], v[58:59], v[62:63]
	v_pk_mul_f32 v[62:63], v[52:53], v[64:65] op_sel_hi:[1,0]
	v_exp_f32_e32 v60, v60
	v_exp_f32_e32 v62, v62
	v_exp_f32_e32 v63, v63
	v_exp_f32_e32 v61, v61
	v_add_f32_e32 v60, 1.0, v60
	v_add_f32_e32 v62, 1.0, v62
	v_add_f32_e32 v63, 1.0, v63
	v_add_f32_e32 v61, 1.0, v61
	v_rcp_f32_e32 v62, v62
	v_rcp_f32_e32 v63, v63
	v_rcp_f32_e32 v60, v60
	v_rcp_f32_e32 v61, v61
	v_pk_mul_f32 v[52:53], v[66:67], v[62:63] op_sel_hi:[0,1]
	v_pk_mul_f32 v[54:55], v[66:67], v[60:61] op_sel_hi:[0,1]
	v_pk_mul_f32 v[54:55], v[50:51], v[54:55]
	v_pk_mul_f32 v[50:51], v[48:49], v[52:53]
	v_cvt_pk_bf16_f32 v48, v56, v57
	v_cvt_pk_bf16_f32 v49, v58, v59
	v_add_u32_e32 v56, 0x80, v146
	v_cvt_pk_bf16_f32 v50, v50, v51
	v_cvt_pk_bf16_f32 v51, v54, v55
	s_waitcnt lgkmcnt(2)
; #define LAS __attribute__((address_space(3)))
; #define PG8_BAR __builtin_amdgcn_s_barrier()
; #define ROW_RS(u, ai, m) row_rs_lds((ai) * 128 + wr * 64 + (m) * 16 + fr, fq)
; #define ROWLOOP for (int ai = 0; ai < 2; ++ai) _Pragma("unroll") for (int m = 0; m < 4; ++m)
; template <class Epi>
; __device__ __forceinline__ void gemm_phase(LAS unsigned char* lds, const int tid, const Gemm g, const StaticOrder& S, const Epi& E) {
;     ...
;         if (!has_next) break;
; #pragma unroll
;         for (int a = 0; a < 2; ++a)
; #pragma unroll
;             for (int b = 0; b < 2; ++b)
; #pragma unroll
;                 for (int m = 0; m < 4; ++m)
; #pragma unroll
;                     for (int n = 0; n < 2; ++n) acc[a][b][m][n] = (f32x4){0.f, 0.f, 0.f, 0.f};
;         cur = nxt; cA = nA; cB = nB; ++ui;
;         if (wr == 1) PG8_BAR;
;     }
; __device__ __forceinline__ float row_rs_lds(int rt, int fq) {
;     extern __shared__ __attribute__((aligned(16))) unsigned char lds_raw_[];
;     const f32x4 v = *(const LAS f32x4*)((LAS unsigned char*)lds_raw_ + RS_OFF + rt * 64 + fq * 16);
;     float s = (v[0] + v[1]) + (v[2] + v[3]);
;     s = red4_sum(s);
;     return __builtin_amdgcn_rsqf(s * (1.0f / D) + EPS);
; }
;     __device__ __forceinline__ void operator()(const Acc& acc, const Unit& u, int wr, int wc, int fr, int fq) const {
;         const int col0 = u.pn * 128 + wc * 32 + fq * 8;
; #pragma unroll
;         ROWLOOP {
;             const int row = ROW_OF(u, ai, m); const float rs = ROW_RS(u, ai, m); const float c1 = -rs * LOG2E, rs2 = rs * rs;
;             f32x4 o[2];
; #pragma unroll
;             for (int n = 0; n < 2; ++n) {
;                 const f32x4 gv = acc[ai][0][m][n], gu = gv * acc[ai][1][m][n], t = gv * c1; f32x4 r;
; #pragma unroll
;                 for (int e = 0; e < 4; ++e) r[e] = __builtin_amdgcn_rcpf(1.0f + __builtin_amdgcn_exp2f(t[e]));
;                 o[n] = gu * (r * rs2);
;             }
;             *(u32x4*)(act + (size_t)row * FF + col0) = pack8(o[0], o[1]);
;         }
	v_add_f32_e32 v52, v208, v209
	v_add_f32_e32 v53, v210, v211
	v_add_f32_e32 v52, v52, v53
	v_mov_b32_e32 v53, v52
	s_nop 1
	v_permlane16_swap_b32_e32 v52, v53
	v_add_f32_e32 v52, v52, v53
	v_mov_b32_e32 v53, v52
	s_nop 1
	v_permlane32_swap_b32_e32 v52, v53
	v_add_f32_e32 v52, v52, v53
	v_fmamk_f32 v52, v52, 0x3a800000, v155
	v_rsq_f32_e32 v54, v52
	v_mad_i64_i32 v[52:53], s[24:25], v56, s53, v[112:113]
	v_lshl_add_u64 v[52:53], v[52:53], 0, v[114:115]
	global_store_dwordx4 v[52:53], v[48:51], off
	s_nop 1
	v_mul_f32_e32 v48, 0xbfb8aa3b, v54
	v_pk_mul_f32 v[50:51], v[44:45], v[48:49] op_sel_hi:[1,0]
	s_nop 0
	v_exp_f32_e32 v49, v50
	v_mul_f32_e32 v50, v54, v54
	v_exp_f32_e32 v51, v51
	v_pk_mul_f32 v[52:53], v[46:47], v[48:49] op_sel_hi:[1,0]
	v_add_f32_e32 v49, 1.0, v49
	v_rcp_f32_e32 v54, v49
	v_exp_f32_e32 v49, v52
	v_exp_f32_e32 v53, v53
	v_add_f32_e32 v51, 1.0, v51
	v_rcp_f32_e32 v55, v51
	v_add_f32_e32 v49, 1.0, v49
	v_rcp_f32_e32 v52, v49
	v_add_f32_e32 v49, 1.0, v53
	v_rcp_f32_e32 v53, v49
	v_pk_mul_f32 v[44:45], v[50:51], v[54:55] op_sel_hi:[0,1]
	v_pk_mul_f32 v[40:41], v[40:41], v[44:45]
	v_pk_mul_f32 v[44:45], v[38:39], v[48:49] op_sel_hi:[1,0]
	v_pk_mul_f32 v[46:47], v[50:51], v[52:53] op_sel_hi:[0,1]
	v_pk_mul_f32 v[42:43], v[42:43], v[46:47]
	v_pk_mul_f32 v[46:47], v[36:37], v[48:49] op_sel_hi:[1,0]
	v_exp_f32_e32 v44, v44
	v_exp_f32_e32 v46, v46
	v_exp_f32_e32 v47, v47
	v_exp_f32_e32 v45, v45
	v_add_f32_e32 v44, 1.0, v44
	v_add_f32_e32 v46, 1.0, v46
	v_add_f32_e32 v47, 1.0, v47
	v_add_f32_e32 v45, 1.0, v45
	v_rcp_f32_e32 v46, v46
	v_rcp_f32_e32 v47, v47
	v_rcp_f32_e32 v44, v44
	v_rcp_f32_e32 v45, v45
	v_pk_mul_f32 v[36:37], v[50:51], v[46:47] op_sel_hi:[0,1]
	v_pk_mul_f32 v[38:39], v[50:51], v[44:45] op_sel_hi:[0,1]
	v_pk_mul_f32 v[38:39], v[34:35], v[38:39]
	v_pk_mul_f32 v[34:35], v[32:33], v[36:37]
	v_cvt_pk_bf16_f32 v32, v40, v41
	v_cvt_pk_bf16_f32 v33, v42, v43
	v_add_u32_e32 v40, 0x90, v146
	v_cvt_pk_bf16_f32 v34, v34, v35
	v_cvt_pk_bf16_f32 v35, v38, v39
	s_waitcnt lgkmcnt(1)
	v_add_f32_e32 v36, v212, v213
	v_add_f32_e32 v37, v214, v215
	v_add_f32_e32 v36, v36, v37
	v_mov_b32_e32 v37, v36
	s_nop 1
	v_permlane16_swap_b32_e32 v36, v37
	v_add_f32_e32 v36, v36, v37
	v_mov_b32_e32 v37, v36
	s_nop 1
	v_permlane32_swap_b32_e32 v36, v37
	v_add_f32_e32 v36, v36, v37
	v_fmamk_f32 v36, v36, 0x3a800000, v155
	v_rsq_f32_e32 v38, v36
	v_mad_i64_i32 v[36:37], s[24:25], v40, s53, v[112:113]
	v_lshl_add_u64 v[36:37], v[36:37], 0, v[114:115]
	global_store_dwordx4 v[36:37], v[32:35], off
	s_nop 1
	v_mul_f32_e32 v32, 0xbfb8aa3b, v38
	v_pk_mul_f32 v[34:35], v[28:29], v[32:33] op_sel_hi:[1,0]
	s_nop 0
	v_exp_f32_e32 v33, v34
	v_mul_f32_e32 v34, v38, v38
	v_exp_f32_e32 v35, v35
	v_pk_mul_f32 v[36:37], v[30:31], v[32:33] op_sel_hi:[1,0]
	v_add_f32_e32 v33, 1.0, v33
	v_rcp_f32_e32 v38, v33
	v_exp_f32_e32 v33, v36
	v_exp_f32_e32 v37, v37
	v_add_f32_e32 v35, 1.0, v35
	v_rcp_f32_e32 v39, v35
	v_add_f32_e32 v33, 1.0, v33
	v_rcp_f32_e32 v36, v33
	v_add_f32_e32 v33, 1.0, v37
	v_rcp_f32_e32 v37, v33
	v_pk_mul_f32 v[28:29], v[34:35], v[38:39] op_sel_hi:[0,1]
	v_pk_mul_f32 v[24:25], v[24:25], v[28:29]
	v_pk_mul_f32 v[28:29], v[22:23], v[32:33] op_sel_hi:[1,0]
	v_pk_mul_f32 v[30:31], v[34:35], v[36:37] op_sel_hi:[0,1]
	v_pk_mul_f32 v[26:27], v[26:27], v[30:31]
	v_pk_mul_f32 v[30:31], v[20:21], v[32:33] op_sel_hi:[1,0]
	v_exp_f32_e32 v28, v28
	v_exp_f32_e32 v30, v30
	v_exp_f32_e32 v31, v31
	v_exp_f32_e32 v29, v29
	v_add_f32_e32 v28, 1.0, v28
	v_add_f32_e32 v30, 1.0, v30
	v_add_f32_e32 v31, 1.0, v31
	v_add_f32_e32 v29, 1.0, v29
	v_rcp_f32_e32 v30, v30
	v_rcp_f32_e32 v31, v31
	v_rcp_f32_e32 v28, v28
	v_rcp_f32_e32 v29, v29
	v_pk_mul_f32 v[20:21], v[34:35], v[30:31] op_sel_hi:[0,1]
	v_pk_mul_f32 v[22:23], v[34:35], v[28:29] op_sel_hi:[0,1]
	v_pk_mul_f32 v[22:23], v[18:19], v[22:23]
	v_pk_mul_f32 v[18:19], v[16:17], v[20:21]
	v_cvt_pk_bf16_f32 v16, v24, v25
	v_cvt_pk_bf16_f32 v17, v26, v27
	v_add_u32_e32 v24, 0xa0, v146
	v_cvt_pk_bf16_f32 v18, v18, v19
	v_cvt_pk_bf16_f32 v19, v22, v23
	s_waitcnt lgkmcnt(0)
	v_add_f32_e32 v20, v216, v217
	v_add_f32_e32 v21, v218, v219
	v_add_f32_e32 v20, v20, v21
	v_mov_b32_e32 v21, v20
	s_nop 1
	v_permlane16_swap_b32_e32 v20, v21
	v_add_f32_e32 v20, v20, v21
	v_mov_b32_e32 v21, v20
	s_nop 1
	v_permlane32_swap_b32_e32 v20, v21
	v_add_f32_e32 v20, v20, v21
	v_fmamk_f32 v20, v20, 0x3a800000, v155
	v_rsq_f32_e32 v22, v20
	v_mad_i64_i32 v[20:21], s[24:25], v24, s53, v[112:113]
	v_lshl_add_u64 v[20:21], v[20:21], 0, v[114:115]
	global_store_dwordx4 v[20:21], v[16:19], off
	s_nop 1
	v_mul_f32_e32 v16, 0xbfb8aa3b, v22
	v_pk_mul_f32 v[18:19], v[12:13], v[16:17] op_sel_hi:[1,0]
	s_nop 0
	v_exp_f32_e32 v17, v18
	v_mul_f32_e32 v18, v22, v22
	v_exp_f32_e32 v19, v19
	v_pk_mul_f32 v[20:21], v[14:15], v[16:17] op_sel_hi:[1,0]
	v_add_f32_e32 v17, 1.0, v17
	v_rcp_f32_e32 v22, v17
	v_exp_f32_e32 v17, v20
	v_exp_f32_e32 v21, v21
	v_add_f32_e32 v19, 1.0, v19
	v_rcp_f32_e32 v23, v19
	v_add_f32_e32 v17, 1.0, v17
	v_rcp_f32_e32 v20, v17
	v_add_f32_e32 v17, 1.0, v21
	v_rcp_f32_e32 v21, v17
	v_pk_mul_f32 v[12:13], v[18:19], v[22:23] op_sel_hi:[0,1]
	v_pk_mul_f32 v[8:9], v[8:9], v[12:13]
	v_pk_mul_f32 v[12:13], v[6:7], v[16:17] op_sel_hi:[1,0]
	v_pk_mul_f32 v[14:15], v[18:19], v[20:21] op_sel_hi:[0,1]
	v_pk_mul_f32 v[10:11], v[10:11], v[14:15]
	v_pk_mul_f32 v[14:15], v[4:5], v[16:17] op_sel_hi:[1,0]
	v_exp_f32_e32 v12, v12
	v_exp_f32_e32 v14, v14
	v_exp_f32_e32 v15, v15
	v_exp_f32_e32 v13, v13
	v_add_f32_e32 v12, 1.0, v12
	v_add_f32_e32 v14, 1.0, v14
	v_add_f32_e32 v15, 1.0, v15
	v_add_f32_e32 v13, 1.0, v13
	v_rcp_f32_e32 v14, v14
	v_rcp_f32_e32 v15, v15
	v_rcp_f32_e32 v12, v12
	v_rcp_f32_e32 v13, v13
	v_pk_mul_f32 v[4:5], v[18:19], v[14:15] op_sel_hi:[0,1]
	v_pk_mul_f32 v[6:7], v[18:19], v[12:13] op_sel_hi:[0,1]
	v_pk_mul_f32 v[6:7], v[2:3], v[6:7]
	v_pk_mul_f32 v[2:3], v[0:1], v[4:5]
	v_add_u32_e32 v4, 0xb0, v146
	v_mad_i64_i32 v[4:5], s[24:25], v4, s53, v[112:113]
	v_lshl_add_u64 v[4:5], v[4:5], 0, v[114:115]
	v_cvt_pk_bf16_f32 v0, v8, v9
	v_cvt_pk_bf16_f32 v1, v10, v11
	v_cvt_pk_bf16_f32 v2, v2, v3
	v_cvt_pk_bf16_f32 v3, v6, v7
	global_store_dwordx4 v[4:5], v[0:3], off
	s_cbranch_vccnz .LBB0_258
	s_andn2_b64 vcc, exec, s[8:9]
	s_cbranch_vccnz .LBB0_257
	s_barrier
	s_branch .LBB0_257
